# GLA prep gate cumsum over the 64 chunk rows as a DPP scan on all four waves (12 columns each) instead of 64 dependent adds on 48 lanes of one wave; last-row total re-read for the boundary store
# baseline (speedup 1.0000x reference)
.LBB0_593:
	ds_read_b128 v[196:199], v83 offset:3072
	ds_read_b128 v[234:237], v83 offset:0
	ds_read_b128 v[238:241], v83 offset:192
	ds_read_b128 v[242:245], v83 offset:384
	ds_read_b128 v[246:249], v83 offset:576
	ds_read_b128 v[250:253], v83 offset:768
	ds_read_b128 v[192:195], v83 offset:960
	ds_read_b128 v[200:203], v83 offset:1152
	ds_read_b128 v[86:89], v83 offset:1344
	s_waitcnt lgkmcnt(4)
	v_pk_fma_f32 v[196:197], v[234:235], v[78:79], v[196:197] op_sel_hi:[1,0,1]
	v_pk_fma_f32 v[198:199], v[236:237], v[78:79], v[198:199] op_sel_hi:[1,0,1]
	v_pk_fma_f32 v[196:197], v[238:239], v[78:79], v[196:197] op_sel:[0,1,0] op_sel_hi:[1,1,1]
	v_pk_fma_f32 v[198:199], v[240:241], v[78:79], v[198:199] op_sel:[0,1,0] op_sel_hi:[1,1,1]
	v_pk_fma_f32 v[196:197], v[242:243], v[80:81], v[196:197] op_sel_hi:[1,0,1]
	v_pk_fma_f32 v[198:199], v[244:245], v[80:81], v[198:199] op_sel_hi:[1,0,1]
	v_pk_fma_f32 v[196:197], v[246:247], v[80:81], v[196:197] op_sel:[0,1,0] op_sel_hi:[1,1,1]
	v_pk_fma_f32 v[198:199], v[248:249], v[80:81], v[198:199] op_sel:[0,1,0] op_sel_hi:[1,1,1]
	ds_read_b128 v[234:237], v83 offset:1536
	ds_read_b128 v[238:241], v83 offset:1728
	ds_read_b128 v[242:245], v83 offset:1920
	ds_read_b128 v[246:249], v83 offset:2112
	s_waitcnt lgkmcnt(4)
	v_pk_fma_f32 v[196:197], v[250:251], v[90:91], v[196:197] op_sel_hi:[1,0,1]
	v_pk_fma_f32 v[198:199], v[252:253], v[90:91], v[198:199] op_sel_hi:[1,0,1]
	v_pk_fma_f32 v[196:197], v[192:193], v[90:91], v[196:197] op_sel:[0,1,0] op_sel_hi:[1,1,1]
	v_pk_fma_f32 v[198:199], v[194:195], v[90:91], v[198:199] op_sel:[0,1,0] op_sel_hi:[1,1,1]
	v_pk_fma_f32 v[196:197], v[200:201], v[2:3], v[196:197] op_sel_hi:[1,0,1]
	v_pk_fma_f32 v[198:199], v[202:203], v[2:3], v[198:199] op_sel_hi:[1,0,1]
	v_pk_fma_f32 v[196:197], v[86:87], v[2:3], v[196:197] op_sel:[0,1,0] op_sel_hi:[1,1,1]
	v_pk_fma_f32 v[198:199], v[88:89], v[2:3], v[198:199] op_sel:[0,1,0] op_sel_hi:[1,1,1]
	ds_read_b128 v[250:253], v83 offset:2304
	ds_read_b128 v[192:195], v83 offset:2496
	ds_read_b128 v[200:203], v83 offset:2688
	ds_read_b128 v[86:89], v83 offset:2880
	s_waitcnt lgkmcnt(4)
	v_pk_fma_f32 v[196:197], v[234:235], v[68:69], v[196:197] op_sel_hi:[1,0,1]
	v_pk_fma_f32 v[198:199], v[236:237], v[68:69], v[198:199] op_sel_hi:[1,0,1]
	v_pk_fma_f32 v[196:197], v[238:239], v[68:69], v[196:197] op_sel:[0,1,0] op_sel_hi:[1,1,1]
	v_pk_fma_f32 v[198:199], v[240:241], v[68:69], v[198:199] op_sel:[0,1,0] op_sel_hi:[1,1,1]
	v_pk_fma_f32 v[196:197], v[242:243], v[70:71], v[196:197] op_sel_hi:[1,0,1]
	v_pk_fma_f32 v[198:199], v[244:245], v[70:71], v[198:199] op_sel_hi:[1,0,1]
	v_pk_fma_f32 v[196:197], v[246:247], v[70:71], v[196:197] op_sel:[0,1,0] op_sel_hi:[1,1,1]
	v_pk_fma_f32 v[198:199], v[248:249], v[70:71], v[198:199] op_sel:[0,1,0] op_sel_hi:[1,1,1]
	s_waitcnt lgkmcnt(0)
	v_pk_fma_f32 v[196:197], v[250:251], v[72:73], v[196:197] op_sel_hi:[1,0,1]
	v_pk_fma_f32 v[198:199], v[252:253], v[72:73], v[198:199] op_sel_hi:[1,0,1]
	v_pk_fma_f32 v[196:197], v[192:193], v[72:73], v[196:197] op_sel:[0,1,0] op_sel_hi:[1,1,1]
	v_pk_fma_f32 v[198:199], v[194:195], v[72:73], v[198:199] op_sel:[0,1,0] op_sel_hi:[1,1,1]
	v_pk_fma_f32 v[196:197], v[200:201], v[74:75], v[196:197] op_sel_hi:[1,0,1]
	v_pk_fma_f32 v[198:199], v[202:203], v[74:75], v[198:199] op_sel_hi:[1,0,1]
	v_pk_fma_f32 v[196:197], v[86:87], v[74:75], v[196:197] op_sel:[0,1,0] op_sel_hi:[1,1,1]
	v_pk_fma_f32 v[198:199], v[88:89], v[74:75], v[198:199] op_sel:[0,1,0] op_sel_hi:[1,1,1]
	v_min_f32_e32 v85, 0, v196
	v_min_f32_e32 v191, 0, v197
	v_min_f32_e32 v107, 0, v198
	v_min_f32_e32 v233, 0, v199
	v_mul_f32_e64 v196, |v196|, s36
	v_mul_f32_e64 v197, |v197|, s36
	v_mul_f32_e64 v198, |v198|, s36
	v_mul_f32_e64 v199, |v199|, s36
	v_exp_f32_e32 v196, v196
	v_exp_f32_e32 v197, v197
	v_exp_f32_e32 v198, v198
	v_exp_f32_e32 v199, v199
	s_nop 0
	v_add_f32_e32 v196, 1.0, v196
	v_add_f32_e32 v197, 1.0, v197
	v_add_f32_e32 v198, 1.0, v198
	v_add_f32_e32 v199, 1.0, v199
	v_log_f32_e32 v196, v196
	v_log_f32_e32 v197, v197
	v_log_f32_e32 v198, v198
	v_log_f32_e32 v199, v199
	s_nop 0
	v_mul_f32_e32 v121, 0x3f317217, v196
	v_mul_f32_e32 v205, 0x3f317217, v197
	v_mul_f32_e32 v204, 0x3f317217, v198
	v_mul_f32_e32 v77, 0x3f317217, v199
	v_fma_f32 v121, v196, s75, -v121
	v_fma_f32 v205, v197, s75, -v205
	v_fma_f32 v204, v198, s75, -v204
	v_fma_f32 v77, v199, s75, -v77
	v_fmac_f32_e32 v121, 0x3377d1cf, v196
	v_fmac_f32_e32 v205, 0x3377d1cf, v197
	v_fmac_f32_e32 v204, 0x3377d1cf, v198
	v_fmac_f32_e32 v77, 0x3377d1cf, v199
	v_fmac_f32_e32 v121, 0x3f317217, v196
	v_fmac_f32_e32 v205, 0x3f317217, v197
	v_fmac_f32_e32 v204, 0x3f317217, v198
	v_fmac_f32_e32 v77, 0x3f317217, v199
	v_sub_f32_e32 v196, v85, v121
	v_sub_f32_e32 v197, v191, v205
	v_sub_f32_e32 v198, v107, v204
	v_sub_f32_e32 v199, v233, v77
	v_mul_f32_e32 v196, 0x3d800000, v196
	v_mul_f32_e32 v197, 0x3d800000, v197
	v_mul_f32_e32 v198, 0x3d800000, v198
	v_mul_f32_e32 v199, 0x3d800000, v199
	ds_write_b32 v84, v196
	ds_write_b32 v84, v197 offset:4
	ds_write_b32 v84, v198 offset:8
	ds_write_b32 v84, v199 offset:12
	ds_read_b128 v[196:199], v83 offset:3088
	ds_read_b128 v[234:237], v83 offset:16
	ds_read_b128 v[238:241], v83 offset:208
	ds_read_b128 v[242:245], v83 offset:400
	ds_read_b128 v[246:249], v83 offset:592
	ds_read_b128 v[250:253], v83 offset:784
	ds_read_b128 v[192:195], v83 offset:976
	ds_read_b128 v[200:203], v83 offset:1168
	ds_read_b128 v[86:89], v83 offset:1360
	s_waitcnt lgkmcnt(4)
	v_pk_fma_f32 v[196:197], v[234:235], v[78:79], v[196:197] op_sel_hi:[1,0,1]
	v_pk_fma_f32 v[198:199], v[236:237], v[78:79], v[198:199] op_sel_hi:[1,0,1]
	v_pk_fma_f32 v[196:197], v[238:239], v[78:79], v[196:197] op_sel:[0,1,0] op_sel_hi:[1,1,1]
	v_pk_fma_f32 v[198:199], v[240:241], v[78:79], v[198:199] op_sel:[0,1,0] op_sel_hi:[1,1,1]
	v_pk_fma_f32 v[196:197], v[242:243], v[80:81], v[196:197] op_sel_hi:[1,0,1]
	v_pk_fma_f32 v[198:199], v[244:245], v[80:81], v[198:199] op_sel_hi:[1,0,1]
	v_pk_fma_f32 v[196:197], v[246:247], v[80:81], v[196:197] op_sel:[0,1,0] op_sel_hi:[1,1,1]
	v_pk_fma_f32 v[198:199], v[248:249], v[80:81], v[198:199] op_sel:[0,1,0] op_sel_hi:[1,1,1]
	ds_read_b128 v[234:237], v83 offset:1552
	ds_read_b128 v[238:241], v83 offset:1744
	ds_read_b128 v[242:245], v83 offset:1936
	ds_read_b128 v[246:249], v83 offset:2128
	s_waitcnt lgkmcnt(4)
	v_pk_fma_f32 v[196:197], v[250:251], v[90:91], v[196:197] op_sel_hi:[1,0,1]
	v_pk_fma_f32 v[198:199], v[252:253], v[90:91], v[198:199] op_sel_hi:[1,0,1]
	v_pk_fma_f32 v[196:197], v[192:193], v[90:91], v[196:197] op_sel:[0,1,0] op_sel_hi:[1,1,1]
	v_pk_fma_f32 v[198:199], v[194:195], v[90:91], v[198:199] op_sel:[0,1,0] op_sel_hi:[1,1,1]
	v_pk_fma_f32 v[196:197], v[200:201], v[2:3], v[196:197] op_sel_hi:[1,0,1]
	v_pk_fma_f32 v[198:199], v[202:203], v[2:3], v[198:199] op_sel_hi:[1,0,1]
	v_pk_fma_f32 v[196:197], v[86:87], v[2:3], v[196:197] op_sel:[0,1,0] op_sel_hi:[1,1,1]
	v_pk_fma_f32 v[198:199], v[88:89], v[2:3], v[198:199] op_sel:[0,1,0] op_sel_hi:[1,1,1]
	ds_read_b128 v[250:253], v83 offset:2320
	ds_read_b128 v[192:195], v83 offset:2512
	ds_read_b128 v[200:203], v83 offset:2704
	ds_read_b128 v[86:89], v83 offset:2896
	s_waitcnt lgkmcnt(4)
	v_pk_fma_f32 v[196:197], v[234:235], v[68:69], v[196:197] op_sel_hi:[1,0,1]
	v_pk_fma_f32 v[198:199], v[236:237], v[68:69], v[198:199] op_sel_hi:[1,0,1]
	v_pk_fma_f32 v[196:197], v[238:239], v[68:69], v[196:197] op_sel:[0,1,0] op_sel_hi:[1,1,1]
	v_pk_fma_f32 v[198:199], v[240:241], v[68:69], v[198:199] op_sel:[0,1,0] op_sel_hi:[1,1,1]
	v_pk_fma_f32 v[196:197], v[242:243], v[70:71], v[196:197] op_sel_hi:[1,0,1]
	v_pk_fma_f32 v[198:199], v[244:245], v[70:71], v[198:199] op_sel_hi:[1,0,1]
	v_pk_fma_f32 v[196:197], v[246:247], v[70:71], v[196:197] op_sel:[0,1,0] op_sel_hi:[1,1,1]
	v_pk_fma_f32 v[198:199], v[248:249], v[70:71], v[198:199] op_sel:[0,1,0] op_sel_hi:[1,1,1]
	s_waitcnt lgkmcnt(0)
	v_pk_fma_f32 v[196:197], v[250:251], v[72:73], v[196:197] op_sel_hi:[1,0,1]
	v_pk_fma_f32 v[198:199], v[252:253], v[72:73], v[198:199] op_sel_hi:[1,0,1]
	v_pk_fma_f32 v[196:197], v[192:193], v[72:73], v[196:197] op_sel:[0,1,0] op_sel_hi:[1,1,1]
	v_pk_fma_f32 v[198:199], v[194:195], v[72:73], v[198:199] op_sel:[0,1,0] op_sel_hi:[1,1,1]
	v_pk_fma_f32 v[196:197], v[200:201], v[74:75], v[196:197] op_sel_hi:[1,0,1]
	v_pk_fma_f32 v[198:199], v[202:203], v[74:75], v[198:199] op_sel_hi:[1,0,1]
	v_pk_fma_f32 v[196:197], v[86:87], v[74:75], v[196:197] op_sel:[0,1,0] op_sel_hi:[1,1,1]
	v_pk_fma_f32 v[198:199], v[88:89], v[74:75], v[198:199] op_sel:[0,1,0] op_sel_hi:[1,1,1]
	v_min_f32_e32 v85, 0, v196
	v_min_f32_e32 v191, 0, v197
	v_min_f32_e32 v107, 0, v198
	v_min_f32_e32 v233, 0, v199
	v_mul_f32_e64 v196, |v196|, s36
	v_mul_f32_e64 v197, |v197|, s36
	v_mul_f32_e64 v198, |v198|, s36
	v_mul_f32_e64 v199, |v199|, s36
	v_exp_f32_e32 v196, v196
	v_exp_f32_e32 v197, v197
	v_exp_f32_e32 v198, v198
	v_exp_f32_e32 v199, v199
	s_nop 0
	v_add_f32_e32 v196, 1.0, v196
	v_add_f32_e32 v197, 1.0, v197
	v_add_f32_e32 v198, 1.0, v198
	v_add_f32_e32 v199, 1.0, v199
	v_log_f32_e32 v196, v196
	v_log_f32_e32 v197, v197
	v_log_f32_e32 v198, v198
	v_log_f32_e32 v199, v199
	s_nop 0
	v_mul_f32_e32 v121, 0x3f317217, v196
	v_mul_f32_e32 v205, 0x3f317217, v197
	v_mul_f32_e32 v204, 0x3f317217, v198
	v_mul_f32_e32 v77, 0x3f317217, v199
	v_fma_f32 v121, v196, s75, -v121
	v_fma_f32 v205, v197, s75, -v205
	v_fma_f32 v204, v198, s75, -v204
	v_fma_f32 v77, v199, s75, -v77
	v_fmac_f32_e32 v121, 0x3377d1cf, v196
	v_fmac_f32_e32 v205, 0x3377d1cf, v197
	v_fmac_f32_e32 v204, 0x3377d1cf, v198
	v_fmac_f32_e32 v77, 0x3377d1cf, v199
	v_fmac_f32_e32 v121, 0x3f317217, v196
	v_fmac_f32_e32 v205, 0x3f317217, v197
	v_fmac_f32_e32 v204, 0x3f317217, v198
	v_fmac_f32_e32 v77, 0x3f317217, v199
	v_sub_f32_e32 v196, v85, v121
	v_sub_f32_e32 v197, v191, v205
	v_sub_f32_e32 v198, v107, v204
	v_sub_f32_e32 v199, v233, v77
	v_mul_f32_e32 v196, 0x3d800000, v196
	v_mul_f32_e32 v197, 0x3d800000, v197
	v_mul_f32_e32 v198, 0x3d800000, v198
	v_mul_f32_e32 v199, 0x3d800000, v199
	ds_write_b32 v84, v196 offset:16
	ds_write_b32 v84, v197 offset:20
	ds_write_b32 v84, v198 offset:24
	ds_write_b32 v84, v199 offset:28
	ds_read_b128 v[196:199], v83 offset:3104
	ds_read_b128 v[234:237], v83 offset:32
	ds_read_b128 v[238:241], v83 offset:224
	ds_read_b128 v[242:245], v83 offset:416
	ds_read_b128 v[246:249], v83 offset:608
	ds_read_b128 v[250:253], v83 offset:800
	ds_read_b128 v[192:195], v83 offset:992
	ds_read_b128 v[200:203], v83 offset:1184
	ds_read_b128 v[86:89], v83 offset:1376
	s_waitcnt lgkmcnt(4)
	v_pk_fma_f32 v[196:197], v[234:235], v[78:79], v[196:197] op_sel_hi:[1,0,1]
	v_pk_fma_f32 v[198:199], v[236:237], v[78:79], v[198:199] op_sel_hi:[1,0,1]
	v_pk_fma_f32 v[196:197], v[238:239], v[78:79], v[196:197] op_sel:[0,1,0] op_sel_hi:[1,1,1]
	v_pk_fma_f32 v[198:199], v[240:241], v[78:79], v[198:199] op_sel:[0,1,0] op_sel_hi:[1,1,1]
	v_pk_fma_f32 v[196:197], v[242:243], v[80:81], v[196:197] op_sel_hi:[1,0,1]
	v_pk_fma_f32 v[198:199], v[244:245], v[80:81], v[198:199] op_sel_hi:[1,0,1]
	v_pk_fma_f32 v[196:197], v[246:247], v[80:81], v[196:197] op_sel:[0,1,0] op_sel_hi:[1,1,1]
	v_pk_fma_f32 v[198:199], v[248:249], v[80:81], v[198:199] op_sel:[0,1,0] op_sel_hi:[1,1,1]
	ds_read_b128 v[234:237], v83 offset:1568
	ds_read_b128 v[238:241], v83 offset:1760
	ds_read_b128 v[242:245], v83 offset:1952
	ds_read_b128 v[246:249], v83 offset:2144
	s_waitcnt lgkmcnt(4)
	v_pk_fma_f32 v[196:197], v[250:251], v[90:91], v[196:197] op_sel_hi:[1,0,1]
	v_pk_fma_f32 v[198:199], v[252:253], v[90:91], v[198:199] op_sel_hi:[1,0,1]
	v_pk_fma_f32 v[196:197], v[192:193], v[90:91], v[196:197] op_sel:[0,1,0] op_sel_hi:[1,1,1]
	v_pk_fma_f32 v[198:199], v[194:195], v[90:91], v[198:199] op_sel:[0,1,0] op_sel_hi:[1,1,1]
	v_pk_fma_f32 v[196:197], v[200:201], v[2:3], v[196:197] op_sel_hi:[1,0,1]
	v_pk_fma_f32 v[198:199], v[202:203], v[2:3], v[198:199] op_sel_hi:[1,0,1]
	v_pk_fma_f32 v[196:197], v[86:87], v[2:3], v[196:197] op_sel:[0,1,0] op_sel_hi:[1,1,1]
	v_pk_fma_f32 v[198:199], v[88:89], v[2:3], v[198:199] op_sel:[0,1,0] op_sel_hi:[1,1,1]
	ds_read_b128 v[250:253], v83 offset:2336
	ds_read_b128 v[192:195], v83 offset:2528
	ds_read_b128 v[200:203], v83 offset:2720
	ds_read_b128 v[86:89], v83 offset:2912
	s_waitcnt lgkmcnt(4)
	v_pk_fma_f32 v[196:197], v[234:235], v[68:69], v[196:197] op_sel_hi:[1,0,1]
	v_pk_fma_f32 v[198:199], v[236:237], v[68:69], v[198:199] op_sel_hi:[1,0,1]
	v_pk_fma_f32 v[196:197], v[238:239], v[68:69], v[196:197] op_sel:[0,1,0] op_sel_hi:[1,1,1]
	v_pk_fma_f32 v[198:199], v[240:241], v[68:69], v[198:199] op_sel:[0,1,0] op_sel_hi:[1,1,1]
	v_pk_fma_f32 v[196:197], v[242:243], v[70:71], v[196:197] op_sel_hi:[1,0,1]
	v_pk_fma_f32 v[198:199], v[244:245], v[70:71], v[198:199] op_sel_hi:[1,0,1]
	v_pk_fma_f32 v[196:197], v[246:247], v[70:71], v[196:197] op_sel:[0,1,0] op_sel_hi:[1,1,1]
	v_pk_fma_f32 v[198:199], v[248:249], v[70:71], v[198:199] op_sel:[0,1,0] op_sel_hi:[1,1,1]
	s_waitcnt lgkmcnt(0)
	v_pk_fma_f32 v[196:197], v[250:251], v[72:73], v[196:197] op_sel_hi:[1,0,1]
	v_pk_fma_f32 v[198:199], v[252:253], v[72:73], v[198:199] op_sel_hi:[1,0,1]
	v_pk_fma_f32 v[196:197], v[192:193], v[72:73], v[196:197] op_sel:[0,1,0] op_sel_hi:[1,1,1]
	v_pk_fma_f32 v[198:199], v[194:195], v[72:73], v[198:199] op_sel:[0,1,0] op_sel_hi:[1,1,1]
	v_pk_fma_f32 v[196:197], v[200:201], v[74:75], v[196:197] op_sel_hi:[1,0,1]
	v_pk_fma_f32 v[198:199], v[202:203], v[74:75], v[198:199] op_sel_hi:[1,0,1]
	v_pk_fma_f32 v[196:197], v[86:87], v[74:75], v[196:197] op_sel:[0,1,0] op_sel_hi:[1,1,1]
	v_pk_fma_f32 v[198:199], v[88:89], v[74:75], v[198:199] op_sel:[0,1,0] op_sel_hi:[1,1,1]
	v_min_f32_e32 v85, 0, v196
	v_min_f32_e32 v191, 0, v197
	v_min_f32_e32 v107, 0, v198
	v_min_f32_e32 v233, 0, v199
	v_mul_f32_e64 v196, |v196|, s36
	v_mul_f32_e64 v197, |v197|, s36
	v_mul_f32_e64 v198, |v198|, s36
	v_mul_f32_e64 v199, |v199|, s36
	v_exp_f32_e32 v196, v196
	v_exp_f32_e32 v197, v197
	v_exp_f32_e32 v198, v198
	v_exp_f32_e32 v199, v199
	s_nop 0
	v_add_f32_e32 v196, 1.0, v196
	v_add_f32_e32 v197, 1.0, v197
	v_add_f32_e32 v198, 1.0, v198
	v_add_f32_e32 v199, 1.0, v199
	v_log_f32_e32 v196, v196
	v_log_f32_e32 v197, v197
	v_log_f32_e32 v198, v198
	v_log_f32_e32 v199, v199
	s_nop 0
	v_mul_f32_e32 v121, 0x3f317217, v196
	v_mul_f32_e32 v205, 0x3f317217, v197
	v_mul_f32_e32 v204, 0x3f317217, v198
	v_mul_f32_e32 v77, 0x3f317217, v199
	v_fma_f32 v121, v196, s75, -v121
	v_fma_f32 v205, v197, s75, -v205
	v_fma_f32 v204, v198, s75, -v204
	v_fma_f32 v77, v199, s75, -v77
	v_fmac_f32_e32 v121, 0x3377d1cf, v196
	v_fmac_f32_e32 v205, 0x3377d1cf, v197
	v_fmac_f32_e32 v204, 0x3377d1cf, v198
	v_fmac_f32_e32 v77, 0x3377d1cf, v199
	v_fmac_f32_e32 v121, 0x3f317217, v196
	v_fmac_f32_e32 v205, 0x3f317217, v197
	v_fmac_f32_e32 v204, 0x3f317217, v198
	v_fmac_f32_e32 v77, 0x3f317217, v199
	v_sub_f32_e32 v196, v85, v121
	v_sub_f32_e32 v197, v191, v205
	v_sub_f32_e32 v198, v107, v204
	v_sub_f32_e32 v199, v233, v77
	v_mul_f32_e32 v196, 0x3d800000, v196
	v_mul_f32_e32 v197, 0x3d800000, v197
	v_mul_f32_e32 v198, 0x3d800000, v198
	v_mul_f32_e32 v199, 0x3d800000, v199
	ds_write_b32 v84, v196 offset:32
	ds_write_b32 v84, v197 offset:36
	ds_write_b32 v84, v198 offset:40
	ds_write_b32 v84, v199 offset:44
	s_waitcnt lgkmcnt(0)
	s_barrier
	v_lshrrev_b32_e32 v2, 6, v123
	s_movk_i32 s38, 0xc4
	v_mul_u32_u24_e32 v2, 48, v2
	v_mad_u32_u24 v2, v209, s38, v2
	v_add_u32_e32 v3, v124, v2
.LBB0_596:
	ds_read_b32 v202, v3
	ds_read_b32 v203, v3 offset:4
	ds_read_b32 v204, v3 offset:8
	ds_read_b32 v205, v3 offset:12
	ds_read_b32 v234, v3 offset:16
	ds_read_b32 v235, v3 offset:20
	ds_read_b32 v236, v3 offset:24
	ds_read_b32 v237, v3 offset:28
	ds_read_b32 v238, v3 offset:32
	ds_read_b32 v239, v3 offset:36
	ds_read_b32 v240, v3 offset:40
	ds_read_b32 v241, v3 offset:44
	s_waitcnt lgkmcnt(0)
	v_add_f32_dpp v202, v202, v202 row_shr:1 row_mask:0xf bank_mask:0xf
	v_add_f32_dpp v203, v203, v203 row_shr:1 row_mask:0xf bank_mask:0xf
	v_add_f32_dpp v204, v204, v204 row_shr:1 row_mask:0xf bank_mask:0xf
	v_add_f32_dpp v205, v205, v205 row_shr:1 row_mask:0xf bank_mask:0xf
	v_add_f32_dpp v234, v234, v234 row_shr:1 row_mask:0xf bank_mask:0xf
	v_add_f32_dpp v235, v235, v235 row_shr:1 row_mask:0xf bank_mask:0xf
	v_add_f32_dpp v236, v236, v236 row_shr:1 row_mask:0xf bank_mask:0xf
	v_add_f32_dpp v237, v237, v237 row_shr:1 row_mask:0xf bank_mask:0xf
	v_add_f32_dpp v238, v238, v238 row_shr:1 row_mask:0xf bank_mask:0xf
	v_add_f32_dpp v239, v239, v239 row_shr:1 row_mask:0xf bank_mask:0xf
	v_add_f32_dpp v240, v240, v240 row_shr:1 row_mask:0xf bank_mask:0xf
	v_add_f32_dpp v241, v241, v241 row_shr:1 row_mask:0xf bank_mask:0xf
	v_add_f32_dpp v202, v202, v202 row_shr:2 row_mask:0xf bank_mask:0xf
	v_add_f32_dpp v203, v203, v203 row_shr:2 row_mask:0xf bank_mask:0xf
	v_add_f32_dpp v204, v204, v204 row_shr:2 row_mask:0xf bank_mask:0xf
	v_add_f32_dpp v205, v205, v205 row_shr:2 row_mask:0xf bank_mask:0xf
	v_add_f32_dpp v234, v234, v234 row_shr:2 row_mask:0xf bank_mask:0xf
	v_add_f32_dpp v235, v235, v235 row_shr:2 row_mask:0xf bank_mask:0xf
	v_add_f32_dpp v236, v236, v236 row_shr:2 row_mask:0xf bank_mask:0xf
	v_add_f32_dpp v237, v237, v237 row_shr:2 row_mask:0xf bank_mask:0xf
	v_add_f32_dpp v238, v238, v238 row_shr:2 row_mask:0xf bank_mask:0xf
	v_add_f32_dpp v239, v239, v239 row_shr:2 row_mask:0xf bank_mask:0xf
	v_add_f32_dpp v240, v240, v240 row_shr:2 row_mask:0xf bank_mask:0xf
	v_add_f32_dpp v241, v241, v241 row_shr:2 row_mask:0xf bank_mask:0xf
	v_add_f32_dpp v202, v202, v202 row_shr:4 row_mask:0xf bank_mask:0xf
	v_add_f32_dpp v203, v203, v203 row_shr:4 row_mask:0xf bank_mask:0xf
	v_add_f32_dpp v204, v204, v204 row_shr:4 row_mask:0xf bank_mask:0xf
	v_add_f32_dpp v205, v205, v205 row_shr:4 row_mask:0xf bank_mask:0xf
	v_add_f32_dpp v234, v234, v234 row_shr:4 row_mask:0xf bank_mask:0xf
	v_add_f32_dpp v235, v235, v235 row_shr:4 row_mask:0xf bank_mask:0xf
	v_add_f32_dpp v236, v236, v236 row_shr:4 row_mask:0xf bank_mask:0xf
	v_add_f32_dpp v237, v237, v237 row_shr:4 row_mask:0xf bank_mask:0xf
	v_add_f32_dpp v238, v238, v238 row_shr:4 row_mask:0xf bank_mask:0xf
	v_add_f32_dpp v239, v239, v239 row_shr:4 row_mask:0xf bank_mask:0xf
	v_add_f32_dpp v240, v240, v240 row_shr:4 row_mask:0xf bank_mask:0xf
	v_add_f32_dpp v241, v241, v241 row_shr:4 row_mask:0xf bank_mask:0xf
	v_add_f32_dpp v202, v202, v202 row_shr:8 row_mask:0xf bank_mask:0xf
	v_add_f32_dpp v203, v203, v203 row_shr:8 row_mask:0xf bank_mask:0xf
	v_add_f32_dpp v204, v204, v204 row_shr:8 row_mask:0xf bank_mask:0xf
	v_add_f32_dpp v205, v205, v205 row_shr:8 row_mask:0xf bank_mask:0xf
	v_add_f32_dpp v234, v234, v234 row_shr:8 row_mask:0xf bank_mask:0xf
	v_add_f32_dpp v235, v235, v235 row_shr:8 row_mask:0xf bank_mask:0xf
	v_add_f32_dpp v236, v236, v236 row_shr:8 row_mask:0xf bank_mask:0xf
	v_add_f32_dpp v237, v237, v237 row_shr:8 row_mask:0xf bank_mask:0xf
	v_add_f32_dpp v238, v238, v238 row_shr:8 row_mask:0xf bank_mask:0xf
	v_add_f32_dpp v239, v239, v239 row_shr:8 row_mask:0xf bank_mask:0xf
	v_add_f32_dpp v240, v240, v240 row_shr:8 row_mask:0xf bank_mask:0xf
	v_add_f32_dpp v241, v241, v241 row_shr:8 row_mask:0xf bank_mask:0xf
	v_add_f32_dpp v202, v202, v202 row_bcast:15 row_mask:0xa bank_mask:0xf
	v_add_f32_dpp v203, v203, v203 row_bcast:15 row_mask:0xa bank_mask:0xf
	v_add_f32_dpp v204, v204, v204 row_bcast:15 row_mask:0xa bank_mask:0xf
	v_add_f32_dpp v205, v205, v205 row_bcast:15 row_mask:0xa bank_mask:0xf
	v_add_f32_dpp v234, v234, v234 row_bcast:15 row_mask:0xa bank_mask:0xf
	v_add_f32_dpp v235, v235, v235 row_bcast:15 row_mask:0xa bank_mask:0xf
	v_add_f32_dpp v236, v236, v236 row_bcast:15 row_mask:0xa bank_mask:0xf
	v_add_f32_dpp v237, v237, v237 row_bcast:15 row_mask:0xa bank_mask:0xf
	v_add_f32_dpp v238, v238, v238 row_bcast:15 row_mask:0xa bank_mask:0xf
	v_add_f32_dpp v239, v239, v239 row_bcast:15 row_mask:0xa bank_mask:0xf
	v_add_f32_dpp v240, v240, v240 row_bcast:15 row_mask:0xa bank_mask:0xf
	v_add_f32_dpp v241, v241, v241 row_bcast:15 row_mask:0xa bank_mask:0xf
	v_add_f32_dpp v202, v202, v202 row_bcast:31 row_mask:0xc bank_mask:0xf
	v_add_f32_dpp v203, v203, v203 row_bcast:31 row_mask:0xc bank_mask:0xf
	v_add_f32_dpp v204, v204, v204 row_bcast:31 row_mask:0xc bank_mask:0xf
	v_add_f32_dpp v205, v205, v205 row_bcast:31 row_mask:0xc bank_mask:0xf
	v_add_f32_dpp v234, v234, v234 row_bcast:31 row_mask:0xc bank_mask:0xf
	v_add_f32_dpp v235, v235, v235 row_bcast:31 row_mask:0xc bank_mask:0xf
	v_add_f32_dpp v236, v236, v236 row_bcast:31 row_mask:0xc bank_mask:0xf
	v_add_f32_dpp v237, v237, v237 row_bcast:31 row_mask:0xc bank_mask:0xf
	v_add_f32_dpp v238, v238, v238 row_bcast:31 row_mask:0xc bank_mask:0xf
	v_add_f32_dpp v239, v239, v239 row_bcast:31 row_mask:0xc bank_mask:0xf
	v_add_f32_dpp v240, v240, v240 row_bcast:31 row_mask:0xc bank_mask:0xf
	v_add_f32_dpp v241, v241, v241 row_bcast:31 row_mask:0xc bank_mask:0xf
	ds_write_b32 v3, v202
	ds_write_b32 v3, v203 offset:4
	ds_write_b32 v3, v204 offset:8
	ds_write_b32 v3, v205 offset:12
	ds_write_b32 v3, v234 offset:16
	ds_write_b32 v3, v235 offset:20
	ds_write_b32 v3, v236 offset:24
	ds_write_b32 v3, v237 offset:28
	ds_write_b32 v3, v238 offset:32
	ds_write_b32 v3, v239 offset:36
	ds_write_b32 v3, v240 offset:40
	ds_write_b32 v3, v241 offset:44
.LBB0_598:
	s_waitcnt lgkmcnt(0)
	s_barrier
	ds_read_b32 v204, v143 offset:12348
	v_lshl_add_u32 v74, v76, 2, v144
	ds_read2_b32 v[2:3], v74 offset1:1
	ds_read2_b32 v[68:69], v74 offset0:2 offset1:3
	ds_read2_b32 v[70:71], v74 offset0:4 offset1:5
	ds_read2_b32 v[72:73], v74 offset0:6 offset1:7
	s_waitcnt lgkmcnt(4)
	s_and_saveexec_b64 s[68:69], s[48:49]
	v_or_b32_e32 v234, s73, v105
	v_ashrrev_i32_e32 v235, 31, v234
	v_lshlrev_b64 v[234:235], 2, v[234:235]
	v_or_b32_e32 v236, v234, v112
	v_mad_u64_u32 v[238:239], s[38:39], v236, s90, v[98:99]
	v_mad_i32_i24 v239, v235, s90, v239
	global_store_dword v[238:239], v204, off
	s_or_b64 exec, exec, s[68:69]
	s_movk_i32 s68, 0x180
	s_waitcnt lgkmcnt(3)
	v_mul_f32_e32 v75, 0x3fb8aa3b, v2
	v_mul_f32_e32 v2, 0xbfb8aa3b, v2
	v_exp_f32_e32 v2, v2
	v_mul_f32_e32 v76, 0x3fb8aa3b, v3
	v_mul_f32_e32 v3, 0xbfb8aa3b, v3
	v_exp_f32_e32 v3, v3
	v_mul_f32_e32 v78, v2, v170
	s_waitcnt lgkmcnt(2)
	v_mul_f32_e32 v2, 0xbfb8aa3b, v68
	v_mul_f32_e32 v77, 0x3fb8aa3b, v68
	v_exp_f32_e32 v2, v2
	v_mul_f32_e32 v68, 0xbfb8aa3b, v69
	v_mul_f32_e32 v80, v3, v171
	v_mul_f32_e32 v3, 0x3fb8aa3b, v69
	v_exp_f32_e32 v68, v68
	s_waitcnt lgkmcnt(1)
	v_mul_f32_e32 v69, 0x3fb8aa3b, v70
	v_exp_f32_e32 v69, v69
	v_exp_f32_e32 v3, v3
	v_mul_f32_e32 v82, v2, v172
	v_mul_f32_e32 v2, 0xbfb8aa3b, v70
	v_mul_f32_e32 v84, v68, v173
	v_exp_f32_e32 v2, v2
	v_mul_f32_e32 v68, 0xbfb8aa3b, v71
	v_mul_f32_e32 v85, v69, v174
	v_exp_f32_e32 v68, v68
	s_waitcnt lgkmcnt(0)
	v_mul_f32_e32 v69, 0x3fb8aa3b, v72
	v_mul_f32_e32 v83, v3, v169
	v_mul_f32_e32 v3, 0x3fb8aa3b, v71
	v_exp_f32_e32 v69, v69
	v_exp_f32_e32 v3, v3
	v_mul_f32_e32 v86, v2, v178
	v_mul_f32_e32 v2, 0xbfb8aa3b, v72
	v_mul_f32_e32 v87, v68, v179
	v_exp_f32_e32 v68, v2
	v_mul_f32_e32 v2, 0x3fb8aa3b, v73
	v_mul_f32_e32 v71, v69, v176
	v_exp_f32_e32 v69, v2
	v_mul_f32_e32 v2, 0xbfb8aa3b, v73
	v_mul_f32_e32 v70, v3, v175
	v_exp_f32_e32 v72, v2
	ds_read2_b32 v[2:3], v74 offset0:8 offset1:9
	v_mul_f32_e32 v88, v68, v180
	v_mul_f32_e32 v89, v69, v177
	v_mul_f32_e32 v90, v72, v181
	ds_read2_b32 v[68:69], v74 offset0:10 offset1:11
	s_waitcnt lgkmcnt(1)
	v_mul_f32_e32 v72, 0x3fb8aa3b, v2
	v_mul_f32_e32 v2, 0xbfb8aa3b, v2
	v_mul_f32_e32 v73, 0x3fb8aa3b, v3
	v_mul_f32_e32 v3, 0xbfb8aa3b, v3
	v_exp_f32_e32 v2, v2
	v_exp_f32_e32 v3, v3
	v_exp_f32_e32 v75, v75
	v_exp_f32_e32 v76, v76
	v_mul_f32_e32 v107, v2, v186
	v_mul_f32_e32 v191, v3, v187
	s_waitcnt lgkmcnt(0)
	v_mul_f32_e32 v2, 0x3fb8aa3b, v68
	v_mul_f32_e32 v3, 0xbfb8aa3b, v68
	v_mul_f32_e32 v68, 0x3fb8aa3b, v69
	v_exp_f32_e32 v68, v68
	v_exp_f32_e32 v77, v77
	v_exp_f32_e32 v2, v2
	v_exp_f32_e32 v3, v3
	v_mul_f32_e32 v69, 0xbfb8aa3b, v69
	v_exp_f32_e32 v72, v72
	v_exp_f32_e32 v73, v73
	v_exp_f32_e32 v69, v69
	v_mul_f32_e32 v194, v68, v185
	v_or_b32_e32 v68, s73, v118
	v_mul_u32_u24_e32 v0, 0x48, v0
	v_mul_f32_e32 v75, v75, v166
	v_mul_f32_e32 v79, v76, v167
	v_mul_f32_e32 v81, v77, v168
	v_mul_f32_e32 v192, v2, v184
	v_mul_f32_e32 v193, v3, v188
	v_mad_u64_u32 v[2:3], s[38:39], v68, s68, v[114:115]
	v_lshl_add_u32 v0, v0, 1, v145
	v_mul_f32_e32 v91, v72, v182
	v_mul_f32_e32 v121, v73, v183
	v_mul_f32_e32 v195, v69, v189
	v_mad_i32_i24 v3, v119, s68, v3
	v_mad_u64_u32 v[76:77], s[38:39], v68, s68, v[116:117]
	v_add_u32_e32 v74, 0x5000, v0
	v_cvt_pk_bf16_f32 v68, v75, v79
	v_cvt_pk_bf16_f32 v69, v81, v83
	v_cvt_pk_bf16_f32 v70, v85, v70
	v_cvt_pk_bf16_f32 v71, v71, v89
	global_store_dwordx4 v[2:3], v[68:71], off
	ds_write2_b64 v74, v[68:69], v[70:71] offset1:1
	v_mad_i32_i24 v77, v119, s68, v77
	v_cvt_pk_bf16_f32 v68, v91, v121
	v_cvt_pk_bf16_f32 v69, v192, v194
	v_add_u32_e32 v196, 0x7400, v0
	v_cvt_pk_bf16_f32 v72, v78, v80
	v_cvt_pk_bf16_f32 v73, v82, v84
	v_cvt_pk_bf16_f32 v74, v86, v87
	v_cvt_pk_bf16_f32 v75, v88, v90
	global_store_dwordx2 v[2:3], v[68:69], off offset:16
	v_cvt_pk_bf16_f32 v2, v107, v191
	v_cvt_pk_bf16_f32 v3, v193, v195
	v_add_u32_e32 v0, 16, v0
	global_store_dwordx4 v[76:77], v[72:75], off
	ds_write2_b64 v196, v[72:73], v[74:75] offset1:1
	global_store_dwordx2 v[76:77], v[2:3], off offset:16
	ds_write2st64_b64 v0, v[68:69], v[2:3] offset0:40 offset1:58
	s_waitcnt lgkmcnt(0)
	s_barrier
	ds_read_b128 v[80:83], v147 offset:20480
	ds_read_b128 v[72:75], v148 offset:29696
	s_waitcnt lgkmcnt(0)
	v_mfma_f32_16x16x32_bf16 v[84:87], v[80:83], v[72:75], 0
	s_mov_b32 s76, s77
	s_mov_b32 s78, s77
	s_mov_b32 s79, s77
	v_mov_b64_e32 v[68:69], s[76:77]
	v_mov_b64_e32 v[70:71], s[78:79]
	s_and_saveexec_b64 s[38:39], s[44:45]
	s_cbranch_execz .LBB0_600
	ds_read_b128 v[68:71], v148 offset:32000
	s_waitcnt lgkmcnt(0)
	v_mfma_f32_16x16x32_bf16 v[68:71], v[80:83], v[68:71], 0
